# attention: LDS-DMA K/V staging with one barrier per tile, K tile swizzled on row&15 so the QK ds_read_b128 are bank-conflict-free
# speedup vs baseline: 1.0006x; 1.0006x over previous
.LBB0_558:
	v_ashrrev_i32_e32 v179, 4, v166
	s_waitcnt vmcnt(7)
	v_and_b32_e32 v4, 0xfffff0, v179
	v_lshlrev_b32_e32 v5, 1, v179
	v_lshlrev_b32_e32 v2, 3, v166
	v_and_or_b32 v4, v5, 8, v4
	v_and_b32_e32 v3, 0x78, v2
	v_lshrrev_b32_e32 v5, 1, v179
	v_lshrrev_b32_e32 v4, 1, v4
	v_bfe_u32 v2, v2, 5, 2
	s_waitcnt vmcnt(6)
	v_and_b32_e32 v6, 3, v179
	v_or_b32_e32 v4, v4, v2
	v_and_or_b32 v5, v5, 4, v6
	v_lshlrev_b32_e32 v130, 1, v3
	v_lshlrev_b32_e32 v4, 9, v4
	v_lshlrev_b32_e32 v5, 6, v5
	v_and_b32_e32 v3, 48, v130
	v_add_u32_e32 v181, 32, v179
	s_waitcnt vmcnt(3)
	v_or3_b32 v18, v4, v5, v3
	v_and_b32_e32 v4, 0xfffff0, v181
	v_lshlrev_b32_e32 v6, 1, v181
	v_and_or_b32 v4, v6, 8, v4
	v_lshrrev_b32_e32 v4, 1, v4
	v_or_b32_e32 v2, v4, v2
	v_and_b32_e32 v165, 63, v166
	v_lshlrev_b32_e32 v2, 9, v2
	v_or3_b32 v19, v2, v5, v3
	v_lshlrev_b32_e32 v3, 4, v165
	s_and_b32 s0, s40, 0x3fffffc0
	v_lshlrev_b32_e32 v2, 3, v165
	v_and_b32_e32 v3, 0xc0, v3
	v_lshlrev_b32_e32 v4, 1, v165
	s_lshl_b32 s0, s0, 2
	v_and_or_b32 v3, v2, 24, v3
	v_and_b32_e32 v4, 32, v4
	v_and_b32_e32 v2, 0x100, v2
	s_add_i32 s70, s0, 0
	v_or3_b32 v171, v3, v4, v2
	v_mad_i64_i32 v[2:3], s[0:1], s28, v179, 0
	v_lshlrev_b64 v[34:35], 1, v[2:3]
	v_lshl_add_u64 v[2:3], s[50:51], 0, v[34:35]
	v_lshl_add_u64 v[2:3], v[2:3], 0, v[130:131]
	global_load_dwordx4 v[2:5], v[2:3], off
	v_mad_i64_i32 v[6:7], s[0:1], s28, v181, 0
	v_lshlrev_b64 v[36:37], 1, v[6:7]
	v_lshl_add_u64 v[6:7], s[50:51], 0, v[36:37]
	v_lshl_add_u64 v[10:11], s[96:97], 0, v[34:35]
	v_lshl_add_u64 v[14:15], s[96:97], 0, v[36:37]
	v_lshl_add_u64 v[6:7], v[6:7], 0, v[130:131]
	v_lshl_add_u64 v[10:11], v[10:11], 0, v[130:131]
	v_lshl_add_u64 v[14:15], v[14:15], 0, v[130:131]
	global_load_dwordx4 v[6:9], v[6:7], off
	v_add_u32_e32 v187, 0, v18
	global_load_dwordx4 v[10:13], v[10:11], off
	v_add_u32_e32 v188, 0, v19
	global_load_dwordx4 v[14:17], v[14:15], off
	s_waitcnt vmcnt(0)
	s_movk_i32 s0, 0xf0
	v_lshl_add_u32 v47, v167, 8, 0
	s_add_i32 s70, s70, 0x10000
	v_add_u32_e32 v176, 0, v171
	v_lshl_add_u32 v177, v167, 2, s70
	s_waitcnt vmcnt(3)
	ds_write_b128 v187, v[2:5]
	v_lshlrev_b32_e32 v2, 8, v179
	v_and_b32_e32 v3, 0xf0, v166
	v_bitop3_b32 v2, v130, v2, v3 bitop3:0xde
	v_add_u32_e32 v191, 0, v2
	v_lshlrev_b32_e32 v2, 8, v181
	v_bitop3_b32 v2, v130, v2, v3 bitop3:0xde
	v_add_u32_e32 v192, 0, v2
	v_lshlrev_b32_e32 v2, 4, v167
	v_and_b32_e32 v46, 0xf0, v2
	s_waitcnt vmcnt(2)
	ds_write_b128 v188, v[6:9]
	v_bitop3_b32 v2, v164, v2, s0 bitop3:0x78
	s_waitcnt vmcnt(1)
	ds_write_b128 v191, v[10:13] offset:32768
	v_add_u32_e32 v180, v47, v2
	s_waitcnt vmcnt(0)
	ds_write_b128 v192, v[14:17] offset:32768
	s_waitcnt lgkmcnt(0)
	s_barrier
	ds_read_b128 v[2:5], v180 offset:32768
	ds_read_b128 v[6:9], v180 offset:40960
	s_waitcnt lgkmcnt(1)
	v_mfma_f32_32x32x16_bf16 v[18:33], v[2:5], v[136:139], 0
	v_bitop3_b32 v38, v164, v46, 32 bitop3:0x36
	v_add_u32_e32 v182, v47, v38
	ds_read_b128 v[38:41], v182 offset:32768
	ds_read_b128 v[42:45], v182 offset:40960
	s_movk_i32 s0, 0x60
	s_waitcnt lgkmcnt(2)
	v_mfma_f32_32x32x16_bf16 v[2:17], v[6:9], v[136:139], 0
	s_waitcnt lgkmcnt(1)
	v_mfma_f32_32x32x16_bf16 v[18:33], v[38:41], v[144:147], v[18:33]
	v_bitop3_b32 v38, v164, v46, 64 bitop3:0x36
	v_add_u32_e32 v183, v47, v38
	s_waitcnt lgkmcnt(0)
	v_mfma_f32_32x32x16_bf16 v[2:17], v[42:45], v[144:147], v[2:17]
	ds_read_b128 v[38:41], v183 offset:32768
	ds_read_b128 v[42:45], v183 offset:40960
	s_waitcnt lgkmcnt(1)
	v_mfma_f32_32x32x16_bf16 v[18:33], v[38:41], v[132:135], v[18:33]
	v_bitop3_b32 v38, v164, v46, s0 bitop3:0x36
	v_add_u32_e32 v184, v47, v38
	s_movk_i32 s0, 0x80
	s_waitcnt lgkmcnt(0)
	v_mfma_f32_32x32x16_bf16 v[2:17], v[42:45], v[132:135], v[2:17]
	ds_read_b128 v[38:41], v184 offset:32768
	ds_read_b128 v[42:45], v184 offset:40960
	s_waitcnt lgkmcnt(1)
	v_mfma_f32_32x32x16_bf16 v[18:33], v[38:41], v[140:143], v[18:33]
	v_bitop3_b32 v38, v164, v46, s0 bitop3:0x36
	v_add_u32_e32 v185, v47, v38
	s_movk_i32 s0, 0xa0
	s_waitcnt lgkmcnt(0)
	v_mfma_f32_32x32x16_bf16 v[2:17], v[42:45], v[140:143], v[2:17]
	ds_read_b128 v[38:41], v185 offset:32768
	ds_read_b128 v[42:45], v185 offset:40960
	s_waitcnt lgkmcnt(1)
	v_mfma_f32_32x32x16_bf16 v[18:33], v[38:41], v[152:155], v[18:33]
	v_bitop3_b32 v38, v164, v46, s0 bitop3:0x36
	v_add_u32_e32 v186, v47, v38
	s_movk_i32 s0, 0xc0
	s_waitcnt lgkmcnt(0)
	v_mfma_f32_32x32x16_bf16 v[2:17], v[42:45], v[152:155], v[2:17]
	ds_read_b128 v[38:41], v186 offset:32768
	ds_read_b128 v[42:45], v186 offset:40960
	s_waitcnt lgkmcnt(1)
	v_mfma_f32_32x32x16_bf16 v[18:33], v[38:41], v[160:163], v[18:33]
	v_bitop3_b32 v38, v164, v46, s0 bitop3:0x36
	v_add_u32_e32 v189, v47, v38
	s_movk_i32 s0, 0xe0
	s_waitcnt lgkmcnt(0)
	v_mfma_f32_32x32x16_bf16 v[2:17], v[42:45], v[160:163], v[2:17]
	ds_read_b128 v[38:41], v189 offset:32768
	ds_read_b128 v[42:45], v189 offset:40960
	s_waitcnt lgkmcnt(1)
	v_mfma_f32_32x32x16_bf16 v[18:33], v[38:41], v[148:151], v[18:33]
	v_bitop3_b32 v38, v164, v46, s0 bitop3:0x36
	v_add_u32_e32 v190, v47, v38
	s_waitcnt lgkmcnt(0)
	v_mfma_f32_32x32x16_bf16 v[2:17], v[42:45], v[148:151], v[2:17]
	ds_read_b128 v[38:41], v190 offset:32768
	ds_read_b128 v[42:45], v190 offset:40960
	s_waitcnt lgkmcnt(1)
	v_mfma_f32_32x32x16_bf16 v[18:33], v[38:41], v[156:159], v[18:33]
	s_waitcnt lgkmcnt(0)
	v_mfma_f32_32x32x16_bf16 v[2:17], v[42:45], v[156:159], v[2:17]
	s_nop 9
	v_max_f32_e32 v38, v19, v19
	v_max_f32_e32 v39, v18, v18
	v_max_f32_e32 v38, v39, v38
	v_max3_f32 v38, v38, v20, v21
	v_max3_f32 v38, v38, v22, v23
	v_max3_f32 v38, v38, v24, v25
	v_max3_f32 v38, v38, v26, v27
	v_max3_f32 v38, v38, v28, v29
	v_max3_f32 v38, v38, v30, v31
	v_max3_f32 v38, v38, v32, v33
	v_max3_f32 v38, v38, v2, v3
	v_max3_f32 v38, v38, v4, v5
	v_max3_f32 v38, v38, v6, v7
	v_max3_f32 v38, v38, v8, v9
	v_max3_f32 v38, v38, v10, v11
	v_max3_f32 v38, v38, v12, v13
	v_max3_f32 v38, v38, v14, v15
	v_max3_f32 v38, v38, v16, v17
	v_mov_b32_e32 v39, v38
	s_nop 1
	v_permlane32_swap_b32_e32 v38, v39
	v_max_f32_e32 v39, v39, v39
	v_max_f32_e32 v38, v38, v38
	v_max_f32_e32 v38, v38, v39
	v_add_f32_e32 v39, 0x7149f2ca, v38
	v_max_f32_e32 v38, 0xf149f2ca, v38
	v_cmp_ge_f32_e32 vcc, s91, v39
	v_sub_f32_e32 v39, 0xf149f2ca, v38
	v_mul_f32_e32 v39, 0x3e0293ee, v39
	s_cmp_eq_u64 vcc, exec
	v_exp_f32_e32 v39, v39
	s_cselect_b64 vcc, -1, 0
	s_lshl_b32 s30, s28, 7
	v_cndmask_b32_e32 v193, v38, v206, vcc
	s_add_u32 s0, s96, s30
	v_mul_f32_e32 v38, 0xbe0293ee, v193
	s_addc_u32 s1, s97, 0
	v_cndmask_b32_e64 v194, v39, 1.0, vcc
	v_mov_b32_e32 v39, v38
	s_add_u32 s30, s50, s30
	v_fmac_f32_e32 v39, 0x3e0293ee, v33
	s_addc_u32 s31, s51, 0
	v_pk_fma_f32 v[98:99], v[2:3], s[90:91], v[38:39] op_sel_hi:[1,0,0]
	v_lshl_add_u64 v[2:3], s[30:31], 0, v[34:35]
	v_pk_fma_f32 v[102:103], v[6:7], s[90:91], v[38:39] op_sel_hi:[1,0,0]
	v_lshl_add_u64 v[2:3], v[2:3], 0, v[130:131]
	v_lshl_add_u64 v[6:7], s[30:31], 0, v[36:37]
	v_pk_fma_f32 v[106:107], v[10:11], s[90:91], v[38:39] op_sel_hi:[1,0,0]
	v_pk_fma_f32 v[100:101], v[4:5], s[90:91], v[38:39] op_sel_hi:[1,0,0]
	global_load_dwordx4 v[2:5], v[2:3], off
	v_lshl_add_u64 v[6:7], v[6:7], 0, v[130:131]
	v_lshl_add_u64 v[10:11], s[0:1], 0, v[34:35]
	v_pk_fma_f32 v[110:111], v[14:15], s[90:91], v[38:39] op_sel_hi:[1,0,0]
	v_pk_fma_f32 v[104:105], v[8:9], s[90:91], v[38:39] op_sel_hi:[1,0,0]
	global_load_dwordx4 v[6:9], v[6:7], off
	v_lshl_add_u64 v[10:11], v[10:11], 0, v[130:131]
	v_lshl_add_u64 v[14:15], s[0:1], 0, v[36:37]
	v_pk_fma_f32 v[108:109], v[12:13], s[90:91], v[38:39] op_sel_hi:[1,0,0]
	global_load_dwordx4 v[10:13], v[10:11], off
	v_lshl_add_u64 v[14:15], v[14:15], 0, v[130:131]
	v_pk_fma_f32 v[112:113], v[16:17], s[90:91], v[38:39] op_sel_hi:[1,0,0]
	global_load_dwordx4 v[14:17], v[14:15], off
	v_fmamk_f32 v18, v18, 0x3e0293ee, v38
	v_fmamk_f32 v19, v19, 0x3e0293ee, v38
	v_fmamk_f32 v20, v20, 0x3e0293ee, v38
	v_fmamk_f32 v21, v21, 0x3e0293ee, v38
	v_fmamk_f32 v22, v22, 0x3e0293ee, v38
	v_fmamk_f32 v23, v23, 0x3e0293ee, v38
	v_fmamk_f32 v24, v24, 0x3e0293ee, v38
	v_fmamk_f32 v25, v25, 0x3e0293ee, v38
	v_fmamk_f32 v26, v26, 0x3e0293ee, v38
	v_fmamk_f32 v27, v27, 0x3e0293ee, v38
	v_fmamk_f32 v28, v28, 0x3e0293ee, v38
	v_fmamk_f32 v29, v29, 0x3e0293ee, v38
	v_fmamk_f32 v30, v30, 0x3e0293ee, v38
	v_fmamk_f32 v31, v31, 0x3e0293ee, v38
	v_fmamk_f32 v32, v32, 0x3e0293ee, v38
	v_exp_f32_e32 v127, v18
	v_exp_f32_e32 v129, v19
	v_exp_f32_e32 v125, v20
	v_exp_f32_e32 v128, v21
	v_exp_f32_e32 v123, v22
	v_exp_f32_e32 v126, v23
	v_exp_f32_e32 v122, v24
	v_exp_f32_e32 v124, v25
	v_exp_f32_e32 v119, v26
	v_exp_f32_e32 v121, v27
	v_exp_f32_e32 v117, v28
	v_exp_f32_e32 v120, v29
	v_exp_f32_e32 v115, v30
	v_exp_f32_e32 v118, v31
	v_exp_f32_e32 v114, v32
	v_exp_f32_e32 v116, v39
	s_waitcnt vmcnt(0)
	s_waitcnt vmcnt(3)
	ds_write_b128 v187, v[2:5] offset:16384
	s_waitcnt vmcnt(2)
	ds_write_b128 v188, v[6:9] offset:16384
	s_waitcnt vmcnt(1)
	ds_write_b128 v191, v[10:13] offset:49152
	s_waitcnt vmcnt(0)
	ds_write_b128 v192, v[14:17] offset:49152
	s_waitcnt lgkmcnt(0)
	s_barrier
	v_mov_b32_e32 v17, 0
	s_cmp_lt_i32 s68, 3
	v_cmp_gt_u32_e64 s[0:1], 32, v165
	s_cbranch_scc1 .LBB0_584
	s_add_i32 s30, 0, 0x4000
	s_cmp_eq_u32 s20, 0
	v_add_u32_e32 v195, s30, v171
	s_cselect_b64 s[30:31], -1, 0
	s_lshl_b32 s38, s63, 6
	s_add_i32 s38, s69, s38
	v_lshlrev_b32_e32 v2, 2, v168
	s_add_i32 s71, s38, s22
	v_mov_b32_e32 v178, 0
	v_sub_u32_e32 v196, s71, v2
	s_sub_i32 s72, 0, s63
	s_lshl_b32 s73, s28, 8
	s_mul_i32 s74, s28, 0x180
	s_mov_b32 s75, 1
	v_mov_b32_e32 v50, 0
	v_mov_b32_e32 v51, v178
	v_mov_b32_e32 v52, v178
	v_mov_b32_e32 v53, v178
	v_mov_b32_e32 v54, v178
	v_mov_b32_e32 v55, v178
	v_mov_b32_e32 v56, v178
	v_mov_b32_e32 v57, v178
	v_mov_b32_e32 v58, v178
	v_mov_b32_e32 v59, v178
	v_mov_b32_e32 v60, v178
	v_mov_b32_e32 v61, v178
	v_mov_b32_e32 v62, v178
	v_mov_b32_e32 v63, v178
	v_mov_b32_e32 v64, v178
	v_mov_b32_e32 v65, v178
	v_mov_b32_e32 v34, 0
	v_mov_b32_e32 v35, v178
	v_mov_b32_e32 v36, v178
	v_mov_b32_e32 v37, v178
	v_mov_b32_e32 v38, v178
	v_mov_b32_e32 v39, v178
	v_mov_b32_e32 v40, v178
	v_mov_b32_e32 v41, v178
	v_mov_b32_e32 v42, v178
	v_mov_b32_e32 v43, v178
	v_mov_b32_e32 v44, v178
	v_mov_b32_e32 v45, v178
	v_mov_b32_e32 v46, v178
	v_mov_b32_e32 v47, v178
	v_mov_b32_e32 v48, v178
	v_mov_b32_e32 v49, v178
	v_mov_b32_e32 v18, 0
	v_mov_b32_e32 v19, v178
	v_mov_b32_e32 v20, v178
	v_mov_b32_e32 v21, v178
	v_mov_b32_e32 v22, v178
	v_mov_b32_e32 v23, v178
	v_mov_b32_e32 v24, v178
	v_mov_b32_e32 v25, v178
	v_mov_b32_e32 v26, v178
	v_mov_b32_e32 v27, v178
	v_mov_b32_e32 v28, v178
	v_mov_b32_e32 v29, v178
	v_mov_b32_e32 v30, v178
	v_mov_b32_e32 v31, v178
	v_mov_b32_e32 v32, v178
	v_mov_b32_e32 v33, v178
	v_mov_b32_e32 v2, 0
	v_mov_b32_e32 v3, v178
	v_mov_b32_e32 v4, v178
	v_mov_b32_e32 v5, v178
	v_mov_b32_e32 v6, v178
	v_mov_b32_e32 v7, v178
	v_mov_b32_e32 v8, v178
	v_mov_b32_e32 v9, v178
	v_mov_b32_e32 v10, v178
	v_mov_b32_e32 v11, v178
	v_mov_b32_e32 v12, v178
	v_mov_b32_e32 v13, v178
	v_mov_b32_e32 v14, v178
	v_mov_b32_e32 v15, v178
	v_mov_b32_e32 v16, v178
	v_mov_b32_e32 v17, v178
	v_mbcnt_lo_u32_b32 v172, -1, 0
	v_mbcnt_hi_u32_b32 v172, -1, v172
	v_lshrrev_b32_e32 v173, 4, v172
	v_and_b32_e32 v250, 15, v172
	v_xor_b32_e32 v250, v250, v173
	s_and_b32 s101, s21, 1
	s_lshl_b32 s101, s101, 3
	v_xor_b32_e32 v250, s101, v250
	v_lshlrev_b32_e32 v251, 4, v250
	s_lshl_b32 s100, s21, 3
	v_add_u32_e32 v250, s100, v173
	s_and_b32 s100, s21, 1
	s_lshl_b32 s100, s100, 2
	s_lshr_b32 s101, s21, 1
	s_lshl_b32 s101, s101, 4
	s_or_b32 s100, s100, s101
	v_bfe_u32 v173, v172, 2, 2
	v_or_b32_e32 v173, s100, v173
	v_bfe_u32 v174, v172, 4, 1
	v_lshl_or_b32 v173, v174, 3, v173
	v_lshl_or_b32 v250, v173, 8, v250
	v_lshrrev_b32_e32 v173, 5, v172
	v_and_b32_e32 v174, 3, v172
	v_lshlrev_b32_e32 v174, 4, v174
	v_lshl_or_b32 v173, v173, 6, v174
	v_lshl_or_b32 v251, v173, 8, v251
